# prologue stagger: workgroups 128-255 run the adaLN GEMV before their weight-transposes items, the others after
# baseline (speedup 1.0000x reference)
; __device__ __forceinline__ void run_transposes(const P& p, unsigned char* lds, int wave, int lane, unsigned mask, int wid, int nw) {
;     float* scr = (float*)(lds + wave * 8448);
;     int base = 0;
; #pragma unroll 1
;     for (int mat = 0; mat < 12; ++mat) {
;         if (!((mask >> mat) & 1u)) continue;
;         const int n = mat_items(mat);
;         int first = (wid - base % nw + nw) % nw;
; #pragma unroll 1
;         for (int it = first; it < n; it += nw) mat_item(p, scr, mat, it, lane);
;         base += n;
;     }
; }
; __device__ __forceinline__ void ph_prologue(const P& p, unsigned char* lds, int tid, int wave, int lane, int G) {
;     run_transposes(p, lds, wave, lane, 0x001u, blockIdx.x * 8 + wave, G * 8);
.Lps_setup:
	v_mov_b32_e32 v1, 0
	v_mov_b32_e32 v146, v184
	s_lshl_b32 s4, s38, 3
	v_readfirstlane_b32 s5, v1
	s_load_dwordx2 s[20:21], s[92:93], s5 offset:0x8
	s_load_dwordx4 s[16:19], s[92:93], s5 offset:0x18
	s_load_dwordx2 s[14:15], s[92:93], s5 offset:0x28
	s_load_dwordx2 s[10:11], s[92:93], s5 offset:0x38
	s_load_dwordx2 s[22:23], s[92:93], s5 offset:0xa8
	v_readfirstlane_b32 s5, v146
	s_ashr_i32 s5, s5, 6
	v_lshlrev_b32_e32 v4, 3, v146
	s_mul_i32 s9, s5, 0x2100
	v_bfe_u32 v9, v146, 3, 3
	v_and_b32_e32 v4, 56, v4
	s_add_i32 s9, s9, 0
	v_mul_u32_u24_e32 v5, 0x84, v4
	v_lshlrev_b32_e32 v6, 2, v9
	v_add3_u32 v10, s9, v5, v6
	v_bfe_i32 v5, v146, 4, 1
	s_abs_i32 s24, s4
	v_and_b32_e32 v11, 0xb00, v5
	v_cvt_f32_u32_e32 v5, s24
	v_and_b32_e32 v1, 63, v146
	v_bfe_u32 v8, v146, 5, 1
	v_lshlrev_b32_e32 v2, 2, v1
	v_lshlrev_b32_e32 v6, 2, v8
	v_add3_u32 v13, s9, v2, v6
	v_rcp_iflag_f32_e32 v6, v5
	v_mov_b32_e32 v3, 0
	v_lshlrev_b32_e32 v2, 1, v4
	s_waitcnt lgkmcnt(0)
	v_lshl_add_u64 v[4:5], s[22:23], 0, v[2:3]
	v_mul_f32_e32 v2, 0x4f7ffffe, v6
	v_cvt_u32_f32_e32 v2, v2
	s_add_i32 s8, s4, s5
	s_lshl_b32 s13, s90, 3
	v_writelane_b32 v253, s13, 2
	s_add_i32 s13, s13, s8
	s_mov_b64 s[8:9], 0x200000
	v_lshl_add_u64 v[4:5], v[4:5], 0, s[8:9]
	s_sub_i32 s8, 0, s24
	v_readfirstlane_b32 s9, v2
	s_mul_i32 s8, s8, s9
	s_mul_hi_u32 s8, s9, s8
	v_writelane_b32 v253, s24, 3
	s_add_i32 s8, s9, s8
	v_and_b32_e32 v12, 3, v146
	v_writelane_b32 v253, s8, 4
	s_lshl_b32 s97, s4, 5
	s_lshl_b32 s70, s4, 4
	s_movk_i32 s24, 0x5800
	s_mov_b32 s25, 0xb000
	s_mov_b32 s26, 0x16000
	s_mov_b32 s27, 0x21000
	s_mov_b32 s28, 0x2c000
	s_mov_b32 s29, 0x37000
	s_mov_b32 s30, 0x42000
	s_mov_b32 s31, 0x4d000
	s_mov_b32 s33, 0x58000
	s_mov_b32 s34, 0x63000
	s_mov_b32 s35, 0x6e000
	s_mov_b32 s40, 0x79000
	s_mov_b32 s41, 0x84000
	s_mov_b32 s42, 0x8f000
	s_mov_b32 s43, 0x9a000
	s_mov_b32 s44, 0xa5000
	s_mov_b32 s45, 0xb0000
	s_mov_b32 s46, 0xbb000
	s_mov_b32 s47, 0xc6000
	s_mov_b32 s48, 0xd1000
	s_mov_b32 s49, 0xdc000
	s_mov_b32 s50, 0xe7000
	s_mov_b32 s51, 0xf2000
	s_mov_b32 s52, 0xfd000
	s_mov_b32 s53, 0x108000
	s_mov_b32 s54, 0x113000
	s_mov_b32 s55, 0x11e000
	s_mov_b32 s56, 0x129000
	s_mov_b32 s57, 0x134000
	s_mov_b32 s58, 0x13f000
	s_mov_b32 s59, 0x14a000
	s_mov_b32 s60, 0x155000
	v_add_u32_e32 v14, 0x400, v13
	v_add_u32_e32 v15, 0x800, v13
	v_add_u32_e32 v16, 0xc00, v13
	v_add_u32_e32 v17, 0x1000, v13
	v_add_u32_e32 v18, 0x1400, v13
	v_add_u32_e32 v19, 0x1800, v13
	v_add_u32_e32 v20, 0x1c00, v13
	s_cmp_lg_u32 s100, 0
	s_cbranch_scc1 .Lps_go
	s_cmp_lt_u32 s90, 0x80
	s_cbranch_scc1 .Lps_go
	s_mov_b32 s100, 1
	s_branch .LBB0_12
.Lps_go:
	s_mov_b32 s61, 0
	s_branch .LBB0_8

; __device__ __forceinline__ float siluf(float v) { return v * __builtin_amdgcn_rcpf(1.f + __expf(-v)); }
; __device__ __forceinline__ void ph_prologue(const P& p, unsigned char* lds, int tid, int wave, int lane, int G) {
;     ...
;     __syncthreads();
;     float* sv = (float*)lds;
;     float* red = (float*)(lds + 36864);
;     bool have = false;
;     typedef float f32x2_ __attribute__((ext_vector_type(2)));
;     for (int task = blockIdx.x; task < 256; task += G) {
;         if (!have) {
;             for (int i = tid; i < 9 * 1024; i += NTHREADS) { const float v = i < 8192 ? p.c[i] : p.c_ctx[i - 8192]; sv[i] = siluf(v); }
;             have = true; __syncthreads();
;         }
;         const int l = task >> 7, c0 = (task & 127) * 72;
;         const bool actv = lane < 36;
;         const float* w = p.ada_w + (size_t)l * DM * 9216 + c0 + 2 * (actv ? lane : 0);
;         float acc0[9], acc1[9];
; #pragma unroll
;         for (int r = 0; r < 9; ++r) { acc0[r] = 0.f; acc1[r] = 0.f; }
;         const int kb = wave * 128;
; #pragma unroll 2
;         for (int k4 = 0; k4 < 128; k4 += 4) {
.LBB0_12:
	s_cmpk_lt_i32 s90, 0x100
	s_cselect_b64 s[8:9], -1, 0
	v_writelane_b32 v253, s8, 5
	s_cmpk_gt_i32 s90, 0xff
	s_nop 0
	v_writelane_b32 v253, s9, 6
	s_barrier
	s_cbranch_scc1 .LBB0_27
	s_cmp_eq_u32 s100, 2
	s_cbranch_scc1 .LBB0_27
	s_lshl_b32 s12, s5, 9
	s_lshl_b32 s24, s5, 7
	s_add_i32 s33, s12, 0
	v_lshlrev_b32_e32 v2, 1, v1
	v_cmp_gt_u32_e64 s[8:9], 36, v1
	s_add_u32 s34, s22, 0x100000
	v_ashrrev_i32_e32 v147, 31, v146
	v_cndmask_b32_e64 v4, 0, v2, s[8:9]
	s_addc_u32 s35, s23, 0
	v_lshl_add_u64 v[2:3], v[146:147], 2, s[20:21]
	s_mul_i32 s20, s5, 0x480000
	s_mul_hi_i32 s21, s24, 0x9000
	s_add_u32 s18, s18, s20
	v_lshlrev_b32_e32 v4, 2, v4
	v_mov_b32_e32 v5, 0
	s_addc_u32 s19, s19, s21
	v_lshl_add_u64 v[6:7], s[18:19], 0, v[4:5]
	s_mov_b64 s[18:19], 0x3f000
	s_movk_i32 s10, 0x2400
	s_movk_i32 s12, 0x288
	v_lshl_add_u32 v8, v1, 3, 0
	s_mul_i32 s26, s5, 0xa20
	v_lshl_add_u64 v[6:7], v[6:7], 0, s[18:19]
	s_movk_i32 s18, 0x8000
	v_cmp_gt_i32_e64 s[10:11], s10, v146
	v_cmp_gt_i32_e64 s[12:13], s12, v146
	v_lshl_add_u32 v1, v146, 2, 0
	s_mov_b32 s5, 0x9000
	s_mov_b64 s[24:25], 0
	s_movk_i32 s40, 0x2000
	s_mov_b32 s19, -1
	s_mov_b64 s[20:21], 0x800
	s_movk_i32 s41, 0x21ff
	s_mov_b32 s42, 0xfffc1000
	s_mov_b32 s43, 0xfffca000
	s_mov_b32 s44, 0xfffd3000
	s_mov_b32 s45, 0xfffdc000
	s_mov_b32 s46, 0xfffe5000
	s_mov_b32 s47, 0xfffee000
	s_mov_b32 s48, 0xffff7000
	s_mov_b64 s[22:23], 0x48000
	v_add_u32_e32 v36, s26, v8
	s_add_i32 s49, 0, 0x9000
	s_mov_b32 s50, 0x38e38e39
	s_movk_i32 s51, 0xffb8
	s_movk_i32 s52, 0x87
	s_mov_b32 s53, s90
	s_mov_b32 s54, s90
	s_branch .LBB0_15
	s_nop 0
	s_nop 0
	s_nop 0
	s_nop 0

; __device__ __forceinline__ float siluf(float v) { return v * __builtin_amdgcn_rcpf(1.f + __expf(-v)); }
; __device__ __forceinline__ void ph_prologue(const P& p, unsigned char* lds, int tid, int wave, int lane, int G) {
;     run_transposes(p, lds, wave, lane, 0x001u, blockIdx.x * 8 + wave, G * 8);
;     __syncthreads();
;     float* sv = (float*)lds;
;     float* red = (float*)(lds + 36864);
;     bool have = false;
;     typedef float f32x2_ __attribute__((ext_vector_type(2)));
;     for (int task = blockIdx.x; task < 256; task += G) {
;         if (!have) {
;             for (int i = tid; i < 9 * 1024; i += NTHREADS) { const float v = i < 8192 ? p.c[i] : p.c_ctx[i - 8192]; sv[i] = siluf(v); }
;             have = true; __syncthreads();
.LBB0_27:
	s_cmp_eq_u32 s100, 1
	s_cbranch_scc0 .Lps_done
	s_mov_b32 s100, 2
	s_mov_b32 s12, 0
	s_mov_b64 exec, -1
	s_waitcnt lgkmcnt(0)
	s_barrier
	s_branch .Lps_setup

; #define REP(k) for (int rep_ = 0; rep_ < (((REPMASK) >> (k)) & 1) + 1; ++rep_)
; __device__ __forceinline__ void ph_normmod(const P& p, const float* srclat, const float* srcctx, int rows, int l, int idx, int gw, int ngw, int lane) {
;     const float* mod = (const float*)(p.ws + WS_MOD) + (size_t)l * 9 * 9216;
;     const float* g = p.norm_g + (l * 3 + idx) * DM;
;     bf16_t* A = (bf16_t*)(p.ws + WS_A);
;     for (int m = gw; m < rows; m += ngw) {
;         const float* src = m < MLAT ? srclat + (size_t)m * DM : srcctx + (size_t)(m - MLAT) * DM;
;         const int mr = m < MLAT ? (m >> 11) : 8;
;         const float* sh = mod + mr * 9216 + (3 * idx) * DM; const float* sc = sh + DM;
; __global__ void __launch_bounds__(NTHREADS) mega_fwd(P p) {
;     ...
;     for (int l = 0; l < 2; ++l) {
;         for (int stg = 0; stg < 3; ++stg) {
;             const bool first = (l == 0 && stg == 0);
;             const int cs = l * 3 + stg;
;             const int rows = (l == 1 && stg == 2) ? MLAT : MALL;
;             PH();
;             if (RUN(1)) REP(1) ph_normmod(q, first ? q.x : HLAT, first ? q.ctx : HCTX, rows, l, stg, gw, ngw, lane);
.LBB0_99:
	v_readlane_b32 s3, v254, 51
	s_or_b32 s2, s24, s3
	s_cmp_eq_u32 s2, 0
	s_cselect_b64 s[6:7], -1, 0
	s_mul_i32 s2, s3, 3
	v_writelane_b32 v255, s6, 2
	s_add_i32 s2, s24, s2
	s_cmp_eq_u32 s24, 2
	v_writelane_b32 v255, s7, 3
	v_readlane_b32 s6, v254, 52
	v_writelane_b32 v255, s2, 4
	s_cselect_b64 s[2:3], -1, 0
	v_readlane_b32 s7, v254, 53
	s_and_b64 s[2:3], s[6:7], s[2:3]
	s_and_b64 s[2:3], s[2:3], exec
	v_mov_b32_e32 v144, v146
	v_mov_b32_e32 v0, v1
	s_cselect_b32 s42, s22, 0x4800
	v_readfirstlane_b32 s2, v144
	s_ashr_i32 s2, s2, 6
	v_readlane_b32 s6, v253, 2
	s_add_i32 s2, s2, s6
	v_writelane_b32 v255, s24, 5
	s_mul_i32 s6, s24, 0xc00
	s_mov_b32 s7, s65
	v_writelane_b32 v255, s6, 6
	v_readfirstlane_b32 s3, v0
	s_cmp_lt_i32 s2, s42
	v_writelane_b32 v255, s7, 7
	v_cmp_lt_i32_e64 s[6:7], v188, v186
	v_cmp_lt_i32_e32 vcc, v187, v186
	s_cbranch_scc0 .LBB0_104
	s_load_dwordx4 s[8:11], s[92:93], s3 offset:0xa0
	s_load_dwordx2 s[12:13], s[92:93], s3 offset:0x0
	s_load_dwordx2 s[16:17], s[92:93], s3 offset:0x10
	s_load_dwordx2 s[18:19], s[92:93], s3 offset:0x30
	v_readlane_b32 s24, v255, 2
	v_readlane_b32 s25, v255, 3
	s_and_b64 s[14:15], s[24:25], exec
	s_waitcnt lgkmcnt(0)
	s_cselect_b32 s20, s13, s9
	s_cselect_b32 s21, s12, s8
	s_add_u32 s3, s10, 0x5300000
	s_addc_u32 s12, s11, 0
	s_and_b64 s[8:9], s[24:25], exec
	s_cselect_b32 s15, s16, s3
	v_readlane_b32 s3, v255, 4
	s_cselect_b32 s14, s17, s12
	s_lshl_b32 s64, s3, 10
	s_lshl_b64 s[8:9], s[64:65], 2
	v_lshlrev_b32_e32 v0, 2, v144
	s_add_u32 s8, s18, s8
	v_readlane_b32 s12, v254, 63
	v_and_b32_e32 v2, 0xfc, v0
	s_addc_u32 s9, s19, s9
	v_readlane_b32 s13, v255, 0
	v_lshlrev_b32_e32 v0, 2, v2
	s_lshl_b64 s[12:13], s[12:13], 2
	v_lshl_add_u64 v[10:11], s[8:9], 0, v[0:1]
	v_cmp_lt_i32_e64 s[8:9], v192, v186
	s_add_u32 s3, s10, s12
	s_addc_u32 s16, s11, s13
	v_cndmask_b32_e64 v0, v185, v192, s[8:9]
	v_cmp_lt_i32_e64 s[8:9], v191, v186
	v_readlane_b32 s12, v255, 6
	v_lshlrev_b32_e32 v14, 2, v0
	v_cndmask_b32_e64 v0, v185, v191, s[8:9]
	v_cmp_lt_i32_e64 s[8:9], v190, v186
	v_readlane_b32 s13, v255, 7
	v_lshlrev_b32_e32 v15, 2, v0
	v_cndmask_b32_e64 v0, v185, v190, s[8:9]
	v_cmp_lt_i32_e64 s[8:9], v189, v186
	s_lshl_b64 s[12:13], s[12:13], 2
	v_lshlrev_b32_e32 v16, 2, v0
	v_cndmask_b32_e64 v0, v185, v189, s[8:9]
	s_add_u32 s3, s3, s12
	v_lshlrev_b32_e32 v17, 2, v0
	v_cndmask_b32_e64 v0, v185, v188, s[6:7]
	s_addc_u32 s12, s16, s13
	v_lshlrev_b32_e32 v18, 2, v0
	v_cndmask_b32_e32 v0, v185, v187, vcc
	s_add_u32 s16, s3, 0x100000
	v_lshlrev_b32_e32 v19, 2, v0
	v_lshlrev_b32_e32 v0, 1, v2
	s_addc_u32 s17, s12, 0
	v_lshl_add_u64 v[12:13], s[10:11], 0, v[0:1]
	s_mov_b64 s[6:7], 0x5b00000
	s_ashr_i32 s3, s2, 31
	v_lshl_add_u64 v[12:13], v[12:13], 0, s[6:7]
	s_lshl_b64 s[6:7], s[2:3], 12
	v_or_b32_e32 v4, 0x100, v2
	v_or_b32_e32 v6, 0x200, v2
	v_or_b32_e32 v8, 0x300, v2
	s_add_u32 s8, s21, s6
	s_addc_u32 s9, s20, s7
	v_lshlrev_b32_e32 v0, 2, v2
	v_lshlrev_b32_e32 v20, 2, v4
	v_lshlrev_b32_e32 v21, 2, v6
	v_lshlrev_b32_e32 v22, 2, v8
	s_branch .LBB0_102
	s_nop 0
	s_nop 0
	s_nop 0
	s_nop 0
	s_nop 0
	s_nop 0
	s_nop 0
	s_nop 0
